# GEMM K-loop: removed hipcc's loop-head s_waitcnt vmcnt(0) (LDS-DMA prefetches now stay in flight across the back-edge as the 8-phase template's counted vmcnt(8) intends)
# speedup vs baseline: 1.0216x; 1.0134x over previous
; #define PG8_STAGE(bufoff, gbase, voff) do { _Pragma("unroll") for (int _i = 0; _i < 2; ++_i) \
;         __builtin_amdgcn_global_load_lds((const unsigned*)((const char*)(gbase) + (voff)[_i]), (LAS unsigned*)(lds + (bufoff) + ldsw + _i * 8192), 16, 0, 0); } while (0)
; #define PG8_LDA(dst, b, h) do { _Pragma("unroll") for (int m = 0; m < 4; ++m) _Pragma("unroll") for (int k = 0; k < 2; ++k) dst[m][k] = *(const LAS bf16x8*)(lds + PG8_SA(b, h) + aoff + m * 2048 + k * 1024); } while (0)
; #define PG8_LDB(dst, b, h) do { _Pragma("unroll") for (int n = 0; n < 2; ++n) _Pragma("unroll") for (int k = 0; k < 2; ++k) dst[n][k] = *(const LAS bf16x8*)(lds + PG8_SB(b, h) + boff + n * 2048 + k * 1024); } while (0)
; #define PG8_MMA(ai, bj, At, Bt) do { __builtin_amdgcn_s_setprio(1); _Pragma("unroll") for (int m = 0; m < 4; ++m) _Pragma("unroll") for (int n = 0; n < 2; ++n) _Pragma("unroll") for (int k = 0; k < 2; ++k) \
;         acc[ai][bj][m][n] = __builtin_amdgcn_mfma_f32_16x16x32_bf16(Bt[n][k], At[m][k], acc[ai][bj][m][n], 0, 0, 0); __builtin_amdgcn_s_setprio(0); } while (0)
; #define PG8_WAIT_V(n) asm volatile("s_waitcnt vmcnt(" #n ")" ::: "memory")
; #define PG8_WAIT_L(n) asm volatile("s_waitcnt lgkmcnt(" #n ")" ::: "memory")
; #define PG8_BAR __builtin_amdgcn_s_barrier()
; #define PG8_SCHED __builtin_amdgcn_sched_barrier(0)
; __device__ __forceinline__ void gemm_phase(LAS unsigned char* lds, const Gemm g, const StaticOrder& S, const Epi& E) {
;     ...
;         for (int t = 0; t < nt; t += 2) {
;             const bool last = (t == nt - 2);
;             const char* a1 = cA + (size_t)(t + 1) * kstep;
;             const char* a2 = last ? nA : cA + (size_t)(t + 2) * kstep; const char* b2 = last ? nB : cB + (size_t)(t + 2) * kstep;
;             const char* a3 = a2 + kstep; const char* b3 = b2 + kstep;
;             PG8_LDB(B0, 0, 0); PG8_LDB(B1, 0, 1); PG8_SCHED; PG8_LDA(At, 0, 0); PG8_STAGE(PG8_SA(1, 1), a1 + hstepA, voffA);
;             PG8_WAIT_V(8); PG8_WAIT_L(0); PG8_BAR; PG8_MMA(0, 0, At, B0); PG8_MMA(0, 1, At, B1); PG8_BAR; PG8_SCHED;
;             PG8_LDA(At, 0, 1); PG8_STAGE(PG8_SB(0, 0), b2, voffB); PG8_STAGE(PG8_SB(0, 1), b2 + hstepB, voffB); PG8_STAGE(PG8_SA(0, 0), a2, voffA);
;             PG8_WAIT_V(8); PG8_WAIT_L(0); PG8_BAR; PG8_MMA(1, 0, At, B0); PG8_MMA(1, 1, At, B1); PG8_BAR; PG8_SCHED;
.LBB0_118:
	s_add_i32 s67, s64, 2
	s_add_u32 vcc_lo, s8, 0x80
	s_addc_u32 s65, s9, 0
	s_add_i32 s62, 0, 0x10000
	s_cmp_eq_u32 s76, s64
	s_cselect_b32 s65, s75, s65
	s_cselect_b32 s64, s74, vcc_lo
	v_add_u32_e32 v96, s62, v181
	s_cselect_b32 vcc_hi, s81, s66
	s_cselect_b32 vcc_lo, s80, s13
	s_add_i32 s63, 0, 0x14000
	ds_read_b128 v[130:133], v96
	ds_read_b128 v[134:137], v96 offset:1024
	ds_read_b128 v[138:141], v96 offset:2048
	ds_read_b128 v[142:145], v96 offset:3072
	v_add_u32_e32 v96, s63, v181
	ds_read_b128 v[146:149], v96
	ds_read_b128 v[150:153], v96 offset:1024
	ds_read_b128 v[168:171], v96 offset:2048
	ds_read_b128 v[172:175], v96 offset:3072
	v_lshl_add_u64 v[238:239], s[8:9], 0, v[166:167]
	s_add_i32 m0, s58, 0xc000
	ds_read_b128 v[176:179], v208
	ds_read_b128 v[210:213], v208 offset:1024
	ds_read_b128 v[214:217], v208 offset:2048
	ds_read_b128 v[218:221], v208 offset:3072
	ds_read_b128 v[222:225], v208 offset:4096
	ds_read_b128 v[226:229], v208 offset:5120
	ds_read_b128 v[230:233], v208 offset:6144
	ds_read_b128 v[234:237], v208 offset:7168
	global_load_lds_dwordx4 v[238:239], off
	v_lshl_add_u64 v[238:239], s[8:9], 0, v[164:165]
	s_add_i32 m0, s58, 0xe000
	s_nop 0
	global_load_lds_dwordx4 v[238:239], off
	s_waitcnt vmcnt(8)
	s_waitcnt lgkmcnt(0)
	s_barrier
	s_setprio 1
	s_waitcnt lgkmcnt(0)
	v_mfma_f32_16x16x32_bf16 v[126:129], v[130:133], v[176:179], v[126:129]
	v_mfma_f32_16x16x32_bf16 v[122:125], v[138:141], v[176:179], v[122:125]
	v_mfma_f32_16x16x32_bf16 v[110:113], v[130:133], v[214:217], v[110:113]
	v_mfma_f32_16x16x32_bf16 v[106:109], v[138:141], v[214:217], v[106:109]
	v_mfma_f32_16x16x32_bf16 v[92:95], v[130:133], v[222:225], v[92:95]
	v_mfma_f32_16x16x32_bf16 v[88:91], v[138:141], v[222:225], v[88:91]
	v_mfma_f32_16x16x32_bf16 v[76:79], v[130:133], v[230:233], v[76:79]
	v_mfma_f32_16x16x32_bf16 v[72:75], v[138:141], v[230:233], v[72:75]
	v_mfma_f32_16x16x32_bf16 v[126:129], v[134:137], v[210:213], v[126:129]
	v_mfma_f32_16x16x32_bf16 v[122:125], v[142:145], v[210:213], v[122:125]
	v_mfma_f32_16x16x32_bf16 v[110:113], v[134:137], v[218:221], v[110:113]
	v_mfma_f32_16x16x32_bf16 v[106:109], v[142:145], v[218:221], v[106:109]
	v_mfma_f32_16x16x32_bf16 v[92:95], v[134:137], v[226:229], v[92:95]
	v_mfma_f32_16x16x32_bf16 v[88:91], v[142:145], v[226:229], v[88:91]
	v_mfma_f32_16x16x32_bf16 v[76:79], v[134:137], v[234:237], v[76:79]
	v_mfma_f32_16x16x32_bf16 v[72:75], v[142:145], v[234:237], v[72:75]
	s_setprio 0
	s_setprio 1
	v_mfma_f32_16x16x32_bf16 v[118:121], v[146:149], v[176:179], v[118:121]
	v_mfma_f32_16x16x32_bf16 v[114:117], v[168:171], v[176:179], v[114:117]
	v_mfma_f32_16x16x32_bf16 v[102:105], v[146:149], v[214:217], v[102:105]
	v_mfma_f32_16x16x32_bf16 v[98:101], v[168:171], v[214:217], v[98:101]
	v_mfma_f32_16x16x32_bf16 v[84:87], v[146:149], v[222:225], v[84:87]
	v_mfma_f32_16x16x32_bf16 v[80:83], v[168:171], v[222:225], v[80:83]
	v_mfma_f32_16x16x32_bf16 v[68:71], v[146:149], v[230:233], v[68:71]
	v_mfma_f32_16x16x32_bf16 v[64:67], v[168:171], v[230:233], v[64:67]
	v_mfma_f32_16x16x32_bf16 v[118:121], v[150:153], v[210:213], v[118:121]
	v_mfma_f32_16x16x32_bf16 v[114:117], v[172:175], v[210:213], v[114:117]
	v_mfma_f32_16x16x32_bf16 v[102:105], v[150:153], v[218:221], v[102:105]
	v_mfma_f32_16x16x32_bf16 v[98:101], v[172:175], v[218:221], v[98:101]
	v_mfma_f32_16x16x32_bf16 v[84:87], v[150:153], v[226:229], v[84:87]
	v_mfma_f32_16x16x32_bf16 v[80:83], v[172:175], v[226:229], v[80:83]
	v_mfma_f32_16x16x32_bf16 v[68:71], v[150:153], v[234:237], v[68:71]
	v_mfma_f32_16x16x32_bf16 v[64:67], v[172:175], v[234:237], v[64:67]
	s_setprio 0
	s_barrier
	s_add_i32 s62, s62, s15
	v_lshl_add_u64 v[238:239], vcc, 0, v[156:157]
	s_mov_b32 m0, s62
	ds_read_b128 v[176:179], v208 offset:16384
	ds_read_b128 v[210:213], v208 offset:17408
	ds_read_b128 v[214:217], v208 offset:18432
	ds_read_b128 v[218:221], v208 offset:19456
	ds_read_b128 v[222:225], v208 offset:20480
	ds_read_b128 v[226:229], v208 offset:21504
	ds_read_b128 v[230:233], v208 offset:22528
	ds_read_b128 v[234:237], v208 offset:23552
	global_load_lds_dwordx4 v[238:239], off
	s_add_i32 m0, s62, 0x2000
	v_lshl_add_u64 v[240:241], vcc, 0, v[160:161]
	s_add_u32 vcc_lo, vcc_lo, s4
	s_addc_u32 vcc_hi, vcc_hi, s5
	s_add_i32 s62, s63, s15
	global_load_lds_dwordx4 v[240:241], off
	v_lshl_add_u64 v[242:243], vcc, 0, v[156:157]
	s_mov_b32 m0, s62
	v_lshl_add_u64 v[244:245], vcc, 0, v[160:161]
	global_load_lds_dwordx4 v[242:243], off
	s_add_i32 m0, s62, 0x2000
	v_lshl_add_u64 v[246:247], s[64:65], 0, v[154:155]
	global_load_lds_dwordx4 v[244:245], off
	s_mov_b32 m0, s58
	v_lshl_add_u64 v[248:249], s[64:65], 0, v[158:159]
	global_load_lds_dwordx4 v[246:247], off
	s_mov_b32 m0, s84
	s_nop 0
	global_load_lds_dwordx4 v[248:249], off
	s_waitcnt vmcnt(8)
	s_waitcnt lgkmcnt(0)
	s_barrier
; #define PG8_STAGE(bufoff, gbase, voff) do { _Pragma("unroll") for (int _i = 0; _i < 2; ++_i) \
;         __builtin_amdgcn_global_load_lds((const unsigned*)((const char*)(gbase) + (voff)[_i]), (LAS unsigned*)(lds + (bufoff) + ldsw + _i * 8192), 16, 0, 0); } while (0)
; #define PG8_LDA(dst, b, h) do { _Pragma("unroll") for (int m = 0; m < 4; ++m) _Pragma("unroll") for (int k = 0; k < 2; ++k) dst[m][k] = *(const LAS bf16x8*)(lds + PG8_SA(b, h) + aoff + m * 2048 + k * 1024); } while (0)
; #define PG8_LDB(dst, b, h) do { _Pragma("unroll") for (int n = 0; n < 2; ++n) _Pragma("unroll") for (int k = 0; k < 2; ++k) dst[n][k] = *(const LAS bf16x8*)(lds + PG8_SB(b, h) + boff + n * 2048 + k * 1024); } while (0)
; #define PG8_MMA(ai, bj, At, Bt) do { __builtin_amdgcn_s_setprio(1); _Pragma("unroll") for (int m = 0; m < 4; ++m) _Pragma("unroll") for (int n = 0; n < 2; ++n) _Pragma("unroll") for (int k = 0; k < 2; ++k) \
;         acc[ai][bj][m][n] = __builtin_amdgcn_mfma_f32_16x16x32_bf16(Bt[n][k], At[m][k], acc[ai][bj][m][n], 0, 0, 0); __builtin_amdgcn_s_setprio(0); } while (0)
; #define PG8_WAIT_V(n) asm volatile("s_waitcnt vmcnt(" #n ")" ::: "memory")
; #define PG8_WAIT_L(n) asm volatile("s_waitcnt lgkmcnt(" #n ")" ::: "memory")
; #define PG8_BAR __builtin_amdgcn_s_barrier()
; #define PG8_SCHED __builtin_amdgcn_sched_barrier(0)
; __device__ __forceinline__ void gemm_phase(LAS unsigned char* lds, const Gemm g, const StaticOrder& S, const Epi& E) {
;     ...
;             PG8_WAIT_V(8); PG8_WAIT_L(0); PG8_BAR; PG8_MMA(1, 0, At, B0); PG8_MMA(1, 1, At, B1); PG8_BAR; PG8_SCHED;
;             PG8_LDB(B0, 1, 0); PG8_LDB(B1, 1, 1); PG8_SCHED; PG8_LDA(At, 1, 0); PG8_STAGE(PG8_SA(0, 1), a2 + hstepA, voffA);
;             PG8_WAIT_V(8); PG8_WAIT_L(0); PG8_BAR; PG8_MMA(0, 0, At, B0); PG8_MMA(0, 1, At, B1); PG8_BAR; PG8_SCHED;
;             PG8_LDA(At, 1, 1); PG8_STAGE(PG8_SB(1, 0), b3, voffB); PG8_STAGE(PG8_SB(1, 1), b3 + hstepB, voffB); PG8_STAGE(PG8_SA(1, 0), a3, voffA);
;             PG8_WAIT_V(8); PG8_WAIT_L(0); PG8_BAR; PG8_MMA(1, 0, At, B0); PG8_MMA(1, 1, At, B1); PG8_BAR; PG8_SCHED;
	s_setprio 1
	s_waitcnt lgkmcnt(0)
	v_mfma_f32_16x16x32_bf16 v[60:63], v[130:133], v[176:179], v[60:63]
	v_mfma_f32_16x16x32_bf16 v[56:59], v[138:141], v[176:179], v[56:59]
	v_mfma_f32_16x16x32_bf16 v[44:47], v[130:133], v[214:217], v[44:47]
	v_mfma_f32_16x16x32_bf16 v[40:43], v[138:141], v[214:217], v[40:43]
	v_mfma_f32_16x16x32_bf16 v[28:31], v[130:133], v[222:225], v[28:31]
	v_mfma_f32_16x16x32_bf16 v[24:27], v[138:141], v[222:225], v[24:27]
	v_mfma_f32_16x16x32_bf16 v[12:15], v[130:133], v[230:233], v[12:15]
	v_mfma_f32_16x16x32_bf16 v[8:11], v[138:141], v[230:233], v[8:11]
	v_mfma_f32_16x16x32_bf16 v[60:63], v[134:137], v[210:213], v[60:63]
	v_mfma_f32_16x16x32_bf16 v[56:59], v[142:145], v[210:213], v[56:59]
	v_mfma_f32_16x16x32_bf16 v[44:47], v[134:137], v[218:221], v[44:47]
	v_mfma_f32_16x16x32_bf16 v[40:43], v[142:145], v[218:221], v[40:43]
	v_mfma_f32_16x16x32_bf16 v[28:31], v[134:137], v[226:229], v[28:31]
	v_mfma_f32_16x16x32_bf16 v[24:27], v[142:145], v[226:229], v[24:27]
	v_mfma_f32_16x16x32_bf16 v[12:15], v[134:137], v[234:237], v[12:15]
	v_mfma_f32_16x16x32_bf16 v[8:11], v[142:145], v[234:237], v[8:11]
	s_setprio 0
	s_setprio 1
	v_mfma_f32_16x16x32_bf16 v[52:55], v[146:149], v[176:179], v[52:55]
	v_mfma_f32_16x16x32_bf16 v[48:51], v[168:171], v[176:179], v[48:51]
	v_mfma_f32_16x16x32_bf16 v[36:39], v[146:149], v[214:217], v[36:39]
	v_mfma_f32_16x16x32_bf16 v[32:35], v[168:171], v[214:217], v[32:35]
	v_mfma_f32_16x16x32_bf16 v[20:23], v[146:149], v[222:225], v[20:23]
	v_mfma_f32_16x16x32_bf16 v[16:19], v[168:171], v[222:225], v[16:19]
	v_mfma_f32_16x16x32_bf16 v[4:7], v[146:149], v[230:233], v[4:7]
	v_mfma_f32_16x16x32_bf16 v[0:3], v[168:171], v[230:233], v[0:3]
	v_mfma_f32_16x16x32_bf16 v[52:55], v[150:153], v[210:213], v[52:55]
	v_mfma_f32_16x16x32_bf16 v[48:51], v[172:175], v[210:213], v[48:51]
	v_mfma_f32_16x16x32_bf16 v[36:39], v[150:153], v[218:221], v[36:39]
	v_mfma_f32_16x16x32_bf16 v[32:35], v[172:175], v[218:221], v[32:35]
	v_mfma_f32_16x16x32_bf16 v[20:23], v[150:153], v[226:229], v[20:23]
	v_mfma_f32_16x16x32_bf16 v[16:19], v[172:175], v[226:229], v[16:19]
	v_mfma_f32_16x16x32_bf16 v[4:7], v[150:153], v[234:237], v[4:7]
	v_mfma_f32_16x16x32_bf16 v[0:3], v[172:175], v[234:237], v[0:3]
	s_setprio 0
	s_barrier
	s_add_i32 s62, 0, 0x18000
	v_add_u32_e32 v96, s62, v181
	s_add_i32 s63, 0, 0x1c000
	ds_read_b128 v[130:133], v96
	ds_read_b128 v[134:137], v96 offset:1024
	ds_read_b128 v[138:141], v96 offset:2048
	ds_read_b128 v[142:145], v96 offset:3072
	v_add_u32_e32 v96, s63, v181
	ds_read_b128 v[146:149], v96
	ds_read_b128 v[150:153], v96 offset:1024
	ds_read_b128 v[168:171], v96 offset:2048
	ds_read_b128 v[172:175], v96 offset:3072
	s_add_u32 s64, s64, s72
	s_addc_u32 s65, s65, s73
	s_mov_b32 m0, s85
	v_lshl_add_u64 v[250:251], s[64:65], 0, v[154:155]
	ds_read_b128 v[176:179], v208 offset:32768
	ds_read_b128 v[210:213], v208 offset:33792
	ds_read_b128 v[214:217], v208 offset:34816
	ds_read_b128 v[218:221], v208 offset:35840
	ds_read_b128 v[222:225], v208 offset:36864
	ds_read_b128 v[226:229], v208 offset:37888
	ds_read_b128 v[230:233], v208 offset:38912
	ds_read_b128 v[234:237], v208 offset:39936
	global_load_lds_dwordx4 v[250:251], off
	v_lshl_add_u64 v[250:251], s[64:65], 0, v[158:159]
	s_mov_b32 m0, s91
	s_nop 0
	global_load_lds_dwordx4 v[250:251], off
	s_waitcnt vmcnt(8)
	s_waitcnt lgkmcnt(0)
	s_barrier
	s_setprio 1
	s_waitcnt lgkmcnt(0)
	v_mfma_f32_16x16x32_bf16 v[126:129], v[130:133], v[176:179], v[126:129]
	v_mfma_f32_16x16x32_bf16 v[122:125], v[138:141], v[176:179], v[122:125]
	v_mfma_f32_16x16x32_bf16 v[110:113], v[130:133], v[214:217], v[110:113]
	v_mfma_f32_16x16x32_bf16 v[106:109], v[138:141], v[214:217], v[106:109]
	v_mfma_f32_16x16x32_bf16 v[92:95], v[130:133], v[222:225], v[92:95]
	v_mfma_f32_16x16x32_bf16 v[88:91], v[138:141], v[222:225], v[88:91]
	v_mfma_f32_16x16x32_bf16 v[76:79], v[130:133], v[230:233], v[76:79]
	v_mfma_f32_16x16x32_bf16 v[72:75], v[138:141], v[230:233], v[72:75]
	v_mfma_f32_16x16x32_bf16 v[126:129], v[134:137], v[210:213], v[126:129]
	v_mfma_f32_16x16x32_bf16 v[122:125], v[142:145], v[210:213], v[122:125]
	v_mfma_f32_16x16x32_bf16 v[110:113], v[134:137], v[218:221], v[110:113]
	v_mfma_f32_16x16x32_bf16 v[106:109], v[142:145], v[218:221], v[106:109]
	v_mfma_f32_16x16x32_bf16 v[92:95], v[134:137], v[226:229], v[92:95]
	v_mfma_f32_16x16x32_bf16 v[88:91], v[142:145], v[226:229], v[88:91]
	v_mfma_f32_16x16x32_bf16 v[76:79], v[134:137], v[234:237], v[76:79]
	v_mfma_f32_16x16x32_bf16 v[72:75], v[142:145], v[234:237], v[72:75]
	s_setprio 0
	s_setprio 1
	v_mfma_f32_16x16x32_bf16 v[118:121], v[146:149], v[176:179], v[118:121]
	v_mfma_f32_16x16x32_bf16 v[114:117], v[168:171], v[176:179], v[114:117]
	v_mfma_f32_16x16x32_bf16 v[102:105], v[146:149], v[214:217], v[102:105]
	v_mfma_f32_16x16x32_bf16 v[98:101], v[168:171], v[214:217], v[98:101]
	v_mfma_f32_16x16x32_bf16 v[84:87], v[146:149], v[222:225], v[84:87]
	v_mfma_f32_16x16x32_bf16 v[80:83], v[168:171], v[222:225], v[80:83]
	v_mfma_f32_16x16x32_bf16 v[68:71], v[146:149], v[230:233], v[68:71]
	v_mfma_f32_16x16x32_bf16 v[64:67], v[168:171], v[230:233], v[64:67]
	v_mfma_f32_16x16x32_bf16 v[118:121], v[150:153], v[210:213], v[118:121]
	v_mfma_f32_16x16x32_bf16 v[114:117], v[172:175], v[210:213], v[114:117]
	v_mfma_f32_16x16x32_bf16 v[102:105], v[150:153], v[218:221], v[102:105]
	v_mfma_f32_16x16x32_bf16 v[98:101], v[172:175], v[218:221], v[98:101]
	v_mfma_f32_16x16x32_bf16 v[84:87], v[150:153], v[226:229], v[84:87]
	v_mfma_f32_16x16x32_bf16 v[80:83], v[172:175], v[226:229], v[80:83]
	v_mfma_f32_16x16x32_bf16 v[68:71], v[150:153], v[234:237], v[68:71]
	v_mfma_f32_16x16x32_bf16 v[64:67], v[172:175], v[234:237], v[64:67]
	s_setprio 0
	s_barrier
; #define PG8_STAGE(bufoff, gbase, voff) do { _Pragma("unroll") for (int _i = 0; _i < 2; ++_i) \
;         __builtin_amdgcn_global_load_lds((const unsigned*)((const char*)(gbase) + (voff)[_i]), (LAS unsigned*)(lds + (bufoff) + ldsw + _i * 8192), 16, 0, 0); } while (0)
; #define PG8_LDA(dst, b, h) do { _Pragma("unroll") for (int m = 0; m < 4; ++m) _Pragma("unroll") for (int k = 0; k < 2; ++k) dst[m][k] = *(const LAS bf16x8*)(lds + PG8_SA(b, h) + aoff + m * 2048 + k * 1024); } while (0)
; #define PG8_MMA(ai, bj, At, Bt) do { __builtin_amdgcn_s_setprio(1); _Pragma("unroll") for (int m = 0; m < 4; ++m) _Pragma("unroll") for (int n = 0; n < 2; ++n) _Pragma("unroll") for (int k = 0; k < 2; ++k) \
;         acc[ai][bj][m][n] = __builtin_amdgcn_mfma_f32_16x16x32_bf16(Bt[n][k], At[m][k], acc[ai][bj][m][n], 0, 0, 0); __builtin_amdgcn_s_setprio(0); } while (0)
; #define PG8_WAIT_V(n) asm volatile("s_waitcnt vmcnt(" #n ")" ::: "memory")
; #define PG8_WAIT_L(n) asm volatile("s_waitcnt lgkmcnt(" #n ")" ::: "memory")
; #define PG8_BAR __builtin_amdgcn_s_barrier()
; #define PG8_SCHED __builtin_amdgcn_sched_barrier(0)
; __device__ __forceinline__ void gemm_phase(LAS unsigned char* lds, const Gemm g, const StaticOrder& S, const Epi& E) {
;     ...
;             PG8_LDA(At, 1, 1); PG8_STAGE(PG8_SB(1, 0), b3, voffB); PG8_STAGE(PG8_SB(1, 1), b3 + hstepB, voffB); PG8_STAGE(PG8_SA(1, 0), a3, voffA);
;             PG8_WAIT_V(8); PG8_WAIT_L(0); PG8_BAR; PG8_MMA(1, 0, At, B0); PG8_MMA(1, 1, At, B1); PG8_BAR; PG8_SCHED;
;         }
;         if (wr == 0) PG8_BAR;
	s_add_i32 s62, s62, s15
	v_lshl_add_u64 v[238:239], v[238:239], 0, s[68:69]
	s_mov_b32 m0, s62
	ds_read_b128 v[176:179], v208 offset:49152
	ds_read_b128 v[210:213], v208 offset:50176
	ds_read_b128 v[214:217], v208 offset:51200
	ds_read_b128 v[218:221], v208 offset:52224
	ds_read_b128 v[222:225], v208 offset:53248
	ds_read_b128 v[226:229], v208 offset:54272
	ds_read_b128 v[230:233], v208 offset:55296
	ds_read_b128 v[234:237], v208 offset:56320
	global_load_lds_dwordx4 v[238:239], off
	v_lshl_add_u64 v[238:239], v[240:241], 0, s[68:69]
	s_add_i32 m0, s62, 0x2000
	s_add_i32 s62, s63, s15
	global_load_lds_dwordx4 v[238:239], off
	v_lshl_add_u64 v[238:239], v[242:243], 0, s[68:69]
	s_mov_b32 m0, s62
	s_nop 0
	global_load_lds_dwordx4 v[238:239], off
	v_lshl_add_u64 v[238:239], v[244:245], 0, s[68:69]
	s_add_i32 m0, s62, 0x2000
	s_nop 0
	global_load_lds_dwordx4 v[238:239], off
	v_lshl_add_u64 v[238:239], v[246:247], 0, s[68:69]
	s_mov_b32 m0, s82
	s_nop 0
	global_load_lds_dwordx4 v[238:239], off
	v_lshl_add_u64 v[238:239], v[248:249], 0, s[68:69]
	s_mov_b32 m0, s56
	s_nop 0
	global_load_lds_dwordx4 v[238:239], off
	s_waitcnt vmcnt(8)
	s_waitcnt lgkmcnt(0)
	s_barrier
	s_setprio 1
	s_waitcnt lgkmcnt(0)
	v_mfma_f32_16x16x32_bf16 v[60:63], v[130:133], v[176:179], v[60:63]
	v_mfma_f32_16x16x32_bf16 v[56:59], v[138:141], v[176:179], v[56:59]
	v_mfma_f32_16x16x32_bf16 v[44:47], v[130:133], v[214:217], v[44:47]
	v_mfma_f32_16x16x32_bf16 v[40:43], v[138:141], v[214:217], v[40:43]
	v_mfma_f32_16x16x32_bf16 v[28:31], v[130:133], v[222:225], v[28:31]
	v_mfma_f32_16x16x32_bf16 v[24:27], v[138:141], v[222:225], v[24:27]
	v_mfma_f32_16x16x32_bf16 v[12:15], v[130:133], v[230:233], v[12:15]
	v_mfma_f32_16x16x32_bf16 v[8:11], v[138:141], v[230:233], v[8:11]
	v_mfma_f32_16x16x32_bf16 v[60:63], v[134:137], v[210:213], v[60:63]
	v_mfma_f32_16x16x32_bf16 v[56:59], v[142:145], v[210:213], v[56:59]
	v_mfma_f32_16x16x32_bf16 v[44:47], v[134:137], v[218:221], v[44:47]
	v_mfma_f32_16x16x32_bf16 v[40:43], v[142:145], v[218:221], v[40:43]
	v_mfma_f32_16x16x32_bf16 v[28:31], v[134:137], v[226:229], v[28:31]
	v_mfma_f32_16x16x32_bf16 v[24:27], v[142:145], v[226:229], v[24:27]
	v_mfma_f32_16x16x32_bf16 v[12:15], v[134:137], v[234:237], v[12:15]
	v_mfma_f32_16x16x32_bf16 v[8:11], v[142:145], v[234:237], v[8:11]
	s_setprio 0
	s_setprio 1
	v_mfma_f32_16x16x32_bf16 v[52:55], v[146:149], v[176:179], v[52:55]
	v_mfma_f32_16x16x32_bf16 v[48:51], v[168:171], v[176:179], v[48:51]
	v_mfma_f32_16x16x32_bf16 v[36:39], v[146:149], v[214:217], v[36:39]
	v_mfma_f32_16x16x32_bf16 v[32:35], v[168:171], v[214:217], v[32:35]
	v_mfma_f32_16x16x32_bf16 v[20:23], v[146:149], v[222:225], v[20:23]
	v_mfma_f32_16x16x32_bf16 v[16:19], v[168:171], v[222:225], v[16:19]
	v_mfma_f32_16x16x32_bf16 v[4:7], v[146:149], v[230:233], v[4:7]
	v_mfma_f32_16x16x32_bf16 v[0:3], v[168:171], v[230:233], v[0:3]
	v_mfma_f32_16x16x32_bf16 v[52:55], v[150:153], v[210:213], v[52:55]
	v_mfma_f32_16x16x32_bf16 v[48:51], v[172:175], v[210:213], v[48:51]
	v_mfma_f32_16x16x32_bf16 v[36:39], v[150:153], v[218:221], v[36:39]
	v_mfma_f32_16x16x32_bf16 v[32:35], v[172:175], v[218:221], v[32:35]
	v_mfma_f32_16x16x32_bf16 v[20:23], v[150:153], v[226:229], v[20:23]
	v_mfma_f32_16x16x32_bf16 v[16:19], v[172:175], v[226:229], v[16:19]
	v_mfma_f32_16x16x32_bf16 v[4:7], v[150:153], v[234:237], v[4:7]
	v_mfma_f32_16x16x32_bf16 v[0:3], v[172:175], v[234:237], v[0:3]
	s_setprio 0
	s_barrier
	s_add_u32 s13, s13, 0x100
	s_addc_u32 s66, s66, 0
	s_add_u32 s8, s8, 0x100
	s_addc_u32 s9, s9, 0
	s_cmp_ge_u32 s67, s40
	s_mov_b32 s64, s67
	s_cbranch_scc0 .LBB0_118
	s_and_b64 vcc, exec, s[2:3]
	s_cbranch_vccz .LBB0_121
	s_barrier
